# prologue weight transposes: touch the rest of each 64-row tile at item start
# speedup vs baseline: 1.0164x; 1.0018x over previous
; template <int MAP> __device__ __forceinline__ void transpose_item(const float* W, int K, int N, bf16_t* WT, const float* gain, LAS float* scr, int item, int lane) {
;     ...
; #pragma unroll 4
;     for (int i = 0; i < 16; ++i) { const int kk = 4 * i + lr; f32x4 v = *(const f32x4*)(W + (size_t)(k0 + kk) * N + n0 + lc); if (gain) v = v * gain[k0 + kk];
;         LAS float* d = scr + kk * 65 + lc; d[0] = v[0]; d[1] = v[1]; d[2] = v[2]; d[3] = v[3]; }
; __device__ __forceinline__ void phase_prologue(const Params& P, LAS unsigned char* lds) {
;     ...
;     for (int it = GWAVE_ID; it < NITEMS; it += GWAVES) {
;         int r = it;
;         if (r < I_EIN) { transpose_item<0>(P.in[6], 2048, EVEN_IN, WB + W_EIN, nmix, scr, r, lane); continue; } r -= I_EIN;
;         if (r < I_UQ) { transpose_item<0>(P.in[10], 512, 1536, WB + W_UQ, P.in[8], scr, r, lane); continue; } r -= I_UQ;
;         if (r < I_UKV) { transpose_item<0>(P.in[11], 512, 2048, WB + W_UKV, P.in[9], scr, r, lane); continue; } r -= I_UKV;
;         if (r < I_EOUT) { transpose_item<0>(P.in[15], 2048, 2048, WB + W_EOUT, nullptr, scr, r, lane); continue; } r -= I_EOUT;
;         if (r < I_OIN) { transpose_item<0>(P.in[16], 2048, ODD_IN, WB + W_OIN, nmix + DM, scr, r, lane); continue; } r -= I_OIN;
;         if (r < I_OOUT) { transpose_item<0>(P.in[17], 4096, 2048, WB + W_OOUT, nullptr, scr, r, lane); continue; } r -= I_OOUT;
;         const int per = 2 * I_G + I_DN + I_PG + I_PP; const int li = r / per; r -= li * per;
;         bf16_t* wgu = WB + (li ? W_GU1 : W_GU0); bf16_t* wdn = WB + (li ? W_DN1 : W_DN0); bf16_t* wpg = WB + (li ? W_PG1 : W_PG0); bf16_t* wpp = WB + (li ? W_PP1 : W_PP0);
;         if (r < I_G) { transpose_item<1>(P.in[18] + (size_t)li * 2048 * DFF, 2048, DFF, wgu, nffn + li * DM, scr, r, lane); continue; } r -= I_G;
;         if (r < I_G) { transpose_item<2>(P.in[19] + (size_t)li * 2048 * DFF, 2048, DFF, wgu, nffn + li * DM, scr, r, lane); continue; } r -= I_G;
;         if (r < I_DN) { transpose_item<0>(P.in[22] + (size_t)li * DFF * 2048, DFF, 2048, wdn, nullptr, scr, r, lane); continue; } r -= I_DN;
;         if (r < I_PG) { transpose_item<0>(P.in[24] + (size_t)li * 2048 * 2048, 2048, 2048, wpg, nple + li * DM, scr, r, lane); continue; } r -= I_PG;
;         transpose_item<0>(P.in[23] + (size_t)li * PLE_DIM * 2048, PLE_DIM, 2048, wpp, nullptr, scr, r, lane);
.LBB0_614:
	s_movk_i32 s0, 0xa1f
	v_cmp_lt_i32_e32 vcc, s0, v13
	s_and_saveexec_b64 s[0:1], vcc
	s_xor_b64 s[10:11], exec, s[0:1]
	s_cbranch_execz .LBB0_712
	s_movk_i32 s0, 0xadf
	v_cmp_lt_u32_e32 vcc, s0, v13
	s_and_saveexec_b64 s[0:1], vcc
	s_xor_b64 s[12:13], exec, s[0:1]
	s_cbranch_execz .LBB0_699
	v_lshlrev_b32_e32 v0, 2, v87
	s_movk_i32 s0, 0xbdf
	v_and_b32_e32 v6, 0x1f00, v0
	v_cmp_lt_u32_e32 vcc, s0, v13
	s_and_saveexec_b64 s[0:1], vcc
	s_xor_b64 s[14:15], exec, s[0:1]
	s_cbranch_execz .LBB0_686
	s_movk_i32 s0, 0xfdf
	v_cmp_lt_u32_e32 vcc, s0, v13
	s_and_saveexec_b64 s[0:1], vcc
	s_xor_b64 s[20:21], exec, s[0:1]
	s_cbranch_execz .LBB0_681
	s_movk_i32 s0, 0x27df
	v_cmp_lt_u32_e32 vcc, s0, v13
	s_and_saveexec_b64 s[0:1], vcc
	s_xor_b64 s[24:25], exec, s[0:1]
	s_cbranch_execz .LBB0_676
	s_movk_i32 s0, 0x2fdf
	v_cmp_lt_u32_e32 vcc, s0, v13
	s_and_saveexec_b64 s[0:1], vcc
	s_xor_b64 s[26:27], exec, s[0:1]
	s_cbranch_execz .LBB0_671
	v_add_u32_e32 v1, 0xffffd020, v13
	s_movk_i32 s0, 0x257f
	v_cmp_lt_u32_e64 s[38:39], s0, v1
	v_mov_b32_e32 v0, 0xffffda80
	s_movk_i32 s0, 0x2580
	v_cndmask_b32_e64 v0, 0, v0, s[38:39]
	v_add_u32_e32 v70, v0, v1
	v_cmp_gt_u32_e64 s[0:1], s0, v1
	v_mov_b32_e32 v1, 0xab80000
	v_mov_b32_e32 v2, 0x2080000
	v_readlane_b32 s2, v254, 21
	v_cndmask_b32_e64 v180, v1, v2, s[0:1]
	v_readlane_b32 s3, v254, 22
	s_nop 1
	v_lshl_add_u64 v[56:57], s[2:3], 0, v[180:181]
	s_movk_i32 s2, 0xaff
	v_cmp_lt_i32_e32 vcc, s2, v70
	s_and_saveexec_b64 s[2:3], vcc
	s_xor_b64 s[28:29], exec, s[2:3]
	s_cbranch_execz .LBB0_658
	s_movk_i32 s2, 0x15ff
	v_cmp_lt_u32_e32 vcc, s2, v70
	s_and_saveexec_b64 s[2:3], vcc
	s_xor_b64 s[30:31], exec, s[2:3]
	s_cbranch_execz .LBB0_645
	s_movk_i32 s2, 0x20ff
	v_cmp_lt_u32_e32 vcc, s2, v70
	s_and_saveexec_b64 s[2:3], vcc
	s_xor_b64 s[34:35], exec, s[2:3]
	s_cbranch_execz .LBB0_640
	s_movk_i32 s2, 0x24ff
	v_cmp_lt_u32_e32 vcc, s2, v70
	s_and_saveexec_b64 s[2:3], vcc
	s_xor_b64 s[40:41], exec, s[2:3]
	s_cbranch_execz .LBB0_627
	v_mov_b32_e32 v1, 0x200000
	v_cndmask_b32_e64 v1, 0, v1, s[38:39]
	v_or_b32_e32 v180, v1, v6
	v_add_u32_e32 v0, v0, v89
	v_mov_b32_e32 v1, 0x1b600
	v_lshl_add_u32 v0, v0, 1, v1
	v_and_b32_e32 v6, 0x1ffc0, v0
	v_or_b32_e32 v0, v88, v6
	v_or_b32_e32 v2, v90, v6
	v_or_b32_e32 v4, v91, v6
	v_or_b32_e32 v6, v12, v6
	v_lshlrev_b32_e32 v0, 13, v0
	v_mov_b32_e32 v1, v181
	v_lshlrev_b32_e32 v2, 13, v2
	v_mov_b32_e32 v3, v181
	v_lshlrev_b32_e32 v4, 13, v4
	v_mov_b32_e32 v5, v181
	v_lshlrev_b32_e32 v6, 13, v6
	v_mov_b32_e32 v7, v181
	v_lshl_add_u64 v[0:1], v[180:181], 0, v[0:1]
	v_lshl_add_u64 v[2:3], v[180:181], 0, v[2:3]
	v_lshl_add_u64 v[4:5], v[180:181], 0, v[4:5]
	v_lshl_add_u64 v[6:7], v[180:181], 0, v[6:7]
	v_lshl_add_u64 v[0:1], v[32:33], 0, v[0:1]
	v_lshl_add_u64 v[2:3], v[32:33], 0, v[2:3]
	v_lshl_add_u64 v[4:5], v[32:33], 0, v[4:5]
	v_lshl_add_u64 v[6:7], v[32:33], 0, v[6:7]
	s_mov_b64 s[42:43], 0
	v_mov_b32_e32 v56, v86
	s_mov_b64 s[42:43], 0x20000
	v_lshl_add_u64 v[112:113], v[6:7], 0, s[42:43]
	global_load_dword v114, v[112:113], off
	v_lshl_add_u64 v[112:113], v[4:5], 0, s[42:43]
	global_load_dword v114, v[112:113], off
	v_lshl_add_u64 v[112:113], v[2:3], 0, s[42:43]
	global_load_dword v114, v[112:113], off
	v_lshl_add_u64 v[112:113], v[0:1], 0, s[42:43]
	global_load_dword v114, v[112:113], off
	s_mov_b64 s[42:43], 0x40000
	v_lshl_add_u64 v[112:113], v[6:7], 0, s[42:43]
	global_load_dword v114, v[112:113], off
	v_lshl_add_u64 v[112:113], v[4:5], 0, s[42:43]
	global_load_dword v114, v[112:113], off
	v_lshl_add_u64 v[112:113], v[2:3], 0, s[42:43]
	global_load_dword v114, v[112:113], off
	v_lshl_add_u64 v[112:113], v[0:1], 0, s[42:43]
	global_load_dword v114, v[112:113], off
	s_mov_b64 s[42:43], 0x60000
	v_lshl_add_u64 v[112:113], v[6:7], 0, s[42:43]
	global_load_dword v114, v[112:113], off
	v_lshl_add_u64 v[112:113], v[4:5], 0, s[42:43]
	global_load_dword v114, v[112:113], off
	v_lshl_add_u64 v[112:113], v[2:3], 0, s[42:43]
	global_load_dword v114, v[112:113], off
	v_lshl_add_u64 v[112:113], v[0:1], 0, s[42:43]
	global_load_dword v114, v[112:113], off
	s_mov_b64 s[42:43], 0

; #define LAS __attribute__((address_space(3)))
; template <int MAP> __device__ __forceinline__ void transpose_item(const float* W, int K, int N, bf16_t* WT, const float* gain, LAS float* scr, int item, int lane) {
;     ...
; #pragma unroll 4
;     for (int i = 0; i < 16; ++i) { const int kk = 4 * i + lr; f32x4 v = *(const f32x4*)(W + (size_t)(k0 + kk) * N + n0 + lc); if (gain) v = v * gain[k0 + kk];
;         LAS float* d = scr + kk * 65 + lc; d[0] = v[0]; d[1] = v[1]; d[2] = v[2]; d[3] = v[3]; }
; __device__ __forceinline__ void phase_prologue(const Params& P, LAS unsigned char* lds) {
;     ...
;         const int per = 2 * I_G + I_DN + I_PG + I_PP; const int li = r / per; r -= li * per;
;         bf16_t* wgu = WB + (li ? W_GU1 : W_GU0); bf16_t* wdn = WB + (li ? W_DN1 : W_DN0); bf16_t* wpg = WB + (li ? W_PG1 : W_PG0); bf16_t* wpp = WB + (li ? W_PP1 : W_PP0);
;         if (r < I_G) { transpose_item<1>(P.in[18] + (size_t)li * 2048 * DFF, 2048, DFF, wgu, nffn + li * DM, scr, r, lane); continue; } r -= I_G;
;         if (r < I_G) { transpose_item<2>(P.in[19] + (size_t)li * 2048 * DFF, 2048, DFF, wgu, nffn + li * DM, scr, r, lane); continue; } r -= I_G;
;         if (r < I_DN) { transpose_item<0>(P.in[22] + (size_t)li * DFF * 2048, DFF, 2048, wdn, nullptr, scr, r, lane); continue; } r -= I_DN;
;         if (r < I_PG) { transpose_item<0>(P.in[24] + (size_t)li * 2048 * 2048, 2048, 2048, wpg, nple + li * DM, scr, r, lane); continue; } r -= I_PG;
;         transpose_item<0>(P.in[23] + (size_t)li * PLE_DIM * 2048, PLE_DIM, 2048, wpp, nullptr, scr, r, lane);
.LBB0_627:
	s_andn2_saveexec_b64 s[42:43], s[40:41]
	s_cbranch_execz .LBB0_639
	v_mov_b32_e32 v1, 0x800
	v_cndmask_b32_e64 v4, 0, v1, s[38:39]
	v_add_u32_e32 v0, v0, v89
	v_mov_b32_e32 v1, 0x1be00
	v_lshl_add_u32 v0, v0, 1, v1
	v_bfe_u32 v5, v0, 6, 11
	v_lshl_or_b32 v2, v4, 13, v6
	v_lshlrev_b32_e32 v6, 6, v5
	v_or_b32_e32 v0, v88, v6
	v_mov_b32_e32 v3, v181
	v_lshlrev_b32_e32 v180, 13, v0
	v_lshl_add_u64 v[0:1], v[2:3], 0, v[180:181]
	v_lshl_add_u64 v[56:57], v[34:35], 0, v[0:1]
	v_lshlrev_b32_e32 v0, 8, v5
	v_mov_b32_e32 v1, v181
	v_lshl_add_u64 v[58:59], v[38:39], 0, v[0:1]
	v_or_b32_e32 v0, v90, v6
	v_lshlrev_b32_e32 v0, 13, v0
	v_lshl_add_u64 v[0:1], v[2:3], 0, v[0:1]
	v_lshl_add_u64 v[60:61], v[34:35], 0, v[0:1]
	v_or_b32_e32 v0, v91, v6
	v_lshlrev_b32_e32 v0, 13, v0
	v_mov_b32_e32 v1, v181
	v_lshlrev_b32_e32 v180, 2, v4
	v_lshl_add_u64 v[0:1], v[2:3], 0, v[0:1]
	v_or_b32_e32 v4, v12, v6
	v_readlane_b32 s52, v253, 26
	v_lshl_add_u64 v[62:63], v[34:35], 0, v[0:1]
	v_lshlrev_b32_e32 v0, 2, v4
	v_mov_b32_e32 v1, v181
	v_readlane_b32 s62, v253, 36
	v_readlane_b32 s63, v253, 37
	v_readlane_b32 s2, v250, 48
	s_mov_b64 s[44:45], 0
	v_lshl_add_u64 v[64:65], s[62:63], 0, v[0:1]
	v_lshlrev_b32_e32 v0, 13, v4
	v_lshl_add_u64 v[0:1], v[2:3], 0, v[0:1]
	v_lshl_add_u64 v[66:67], v[34:35], 0, v[0:1]
	v_mov_b32_e32 v71, v86
	v_readlane_b32 s3, v250, 49
	v_readlane_b32 s53, v253, 27
	v_readlane_b32 s54, v253, 28
	v_readlane_b32 s55, v253, 29
	v_readlane_b32 s56, v253, 30
	v_readlane_b32 s57, v253, 31
	v_readlane_b32 s58, v253, 32
	v_readlane_b32 s59, v253, 33
	v_readlane_b32 s60, v253, 34
	v_readlane_b32 s61, v253, 35
	v_readlane_b32 s64, v253, 38
	v_readlane_b32 s65, v253, 39
	v_readlane_b32 s66, v253, 40
	v_readlane_b32 s67, v253, 41
	s_mov_b64 s[44:45], 0x20000
	v_lshl_add_u64 v[112:113], v[66:67], 0, s[44:45]
	global_load_dword v114, v[112:113], off
	v_lshl_add_u64 v[112:113], v[62:63], 0, s[44:45]
	global_load_dword v114, v[112:113], off
	v_lshl_add_u64 v[112:113], v[60:61], 0, s[44:45]
	global_load_dword v114, v[112:113], off
	v_lshl_add_u64 v[112:113], v[56:57], 0, s[44:45]
	global_load_dword v114, v[112:113], off
	s_mov_b64 s[44:45], 0x40000
	v_lshl_add_u64 v[112:113], v[66:67], 0, s[44:45]
	global_load_dword v114, v[112:113], off
	v_lshl_add_u64 v[112:113], v[62:63], 0, s[44:45]
	global_load_dword v114, v[112:113], off
	v_lshl_add_u64 v[112:113], v[60:61], 0, s[44:45]
	global_load_dword v114, v[112:113], off
	v_lshl_add_u64 v[112:113], v[56:57], 0, s[44:45]
	global_load_dword v114, v[112:113], off
	s_mov_b64 s[44:45], 0x60000
	v_lshl_add_u64 v[112:113], v[66:67], 0, s[44:45]
	global_load_dword v114, v[112:113], off
	v_lshl_add_u64 v[112:113], v[62:63], 0, s[44:45]
	global_load_dword v114, v[112:113], off
	v_lshl_add_u64 v[112:113], v[60:61], 0, s[44:45]
	global_load_dword v114, v[112:113], off
	v_lshl_add_u64 v[112:113], v[56:57], 0, s[44:45]
	global_load_dword v114, v[112:113], off
	s_mov_b64 s[44:45], 0
	s_branch .LBB0_630

; #define LAS __attribute__((address_space(3)))
; template <int MAP> __device__ __forceinline__ void transpose_item(const float* W, int K, int N, bf16_t* WT, const float* gain, LAS float* scr, int item, int lane) {
;     ...
; #pragma unroll 4
;     for (int i = 0; i < 16; ++i) { const int kk = 4 * i + lr; f32x4 v = *(const f32x4*)(W + (size_t)(k0 + kk) * N + n0 + lc); if (gain) v = v * gain[k0 + kk];
;         LAS float* d = scr + kk * 65 + lc; d[0] = v[0]; d[1] = v[1]; d[2] = v[2]; d[3] = v[3]; }
; __device__ __forceinline__ void phase_prologue(const Params& P, LAS unsigned char* lds) {
;     ...
;         const int per = 2 * I_G + I_DN + I_PG + I_PP; const int li = r / per; r -= li * per;
;         bf16_t* wgu = WB + (li ? W_GU1 : W_GU0); bf16_t* wdn = WB + (li ? W_DN1 : W_DN0); bf16_t* wpg = WB + (li ? W_PG1 : W_PG0); bf16_t* wpp = WB + (li ? W_PP1 : W_PP0);
;         if (r < I_G) { transpose_item<1>(P.in[18] + (size_t)li * 2048 * DFF, 2048, DFF, wgu, nffn + li * DM, scr, r, lane); continue; } r -= I_G;
;         if (r < I_G) { transpose_item<2>(P.in[19] + (size_t)li * 2048 * DFF, 2048, DFF, wgu, nffn + li * DM, scr, r, lane); continue; } r -= I_G;
;         if (r < I_DN) { transpose_item<0>(P.in[22] + (size_t)li * DFF * 2048, DFF, 2048, wdn, nullptr, scr, r, lane); continue; } r -= I_DN;
;         if (r < I_PG) { transpose_item<0>(P.in[24] + (size_t)li * 2048 * 2048, 2048, 2048, wpg, nple + li * DM, scr, r, lane); continue; } r -= I_PG;
;         transpose_item<0>(P.in[23] + (size_t)li * PLE_DIM * 2048, PLE_DIM, 2048, wpp, nullptr, scr, r, lane);
.LBB0_640:
	s_andn2_saveexec_b64 s[34:35], s[34:35]
	s_cbranch_execz .LBB0_644
	v_mov_b32_e32 v1, 0x2c00000
	v_cndmask_b32_e64 v1, 0, v1, s[38:39]
	v_or_b32_e32 v180, v1, v6
	v_add_u32_e32 v0, v0, v89
	v_mov_b32_e32 v1, 0x1d400
	v_lshl_add_u32 v0, v0, 1, v1
	v_and_b32_e32 v6, 0x1ffc0, v0
	v_or_b32_e32 v0, v88, v6
	v_or_b32_e32 v2, v90, v6
	v_or_b32_e32 v4, v91, v6
	v_or_b32_e32 v6, v12, v6
	v_lshlrev_b32_e32 v0, 13, v0
	v_mov_b32_e32 v1, v181
	v_lshlrev_b32_e32 v2, 13, v2
	v_mov_b32_e32 v3, v181
	v_lshlrev_b32_e32 v4, 13, v4
	v_mov_b32_e32 v5, v181
	v_lshlrev_b32_e32 v6, 13, v6
	v_mov_b32_e32 v7, v181
	v_lshl_add_u64 v[0:1], v[180:181], 0, v[0:1]
	v_lshl_add_u64 v[2:3], v[180:181], 0, v[2:3]
	v_lshl_add_u64 v[4:5], v[180:181], 0, v[4:5]
	v_lshl_add_u64 v[6:7], v[180:181], 0, v[6:7]
	v_lshl_add_u64 v[0:1], v[40:41], 0, v[0:1]
	v_lshl_add_u64 v[2:3], v[40:41], 0, v[2:3]
	v_lshl_add_u64 v[4:5], v[40:41], 0, v[4:5]
	v_lshl_add_u64 v[6:7], v[40:41], 0, v[6:7]
	s_mov_b64 s[40:41], 0
	v_mov_b32_e32 v56, v86
	s_mov_b64 s[40:41], 0x20000
	v_lshl_add_u64 v[112:113], v[6:7], 0, s[40:41]
	global_load_dword v114, v[112:113], off
	v_lshl_add_u64 v[112:113], v[4:5], 0, s[40:41]
	global_load_dword v114, v[112:113], off
	v_lshl_add_u64 v[112:113], v[2:3], 0, s[40:41]
	global_load_dword v114, v[112:113], off
	v_lshl_add_u64 v[112:113], v[0:1], 0, s[40:41]
	global_load_dword v114, v[112:113], off
	s_mov_b64 s[40:41], 0x40000
	v_lshl_add_u64 v[112:113], v[6:7], 0, s[40:41]
	global_load_dword v114, v[112:113], off
	v_lshl_add_u64 v[112:113], v[4:5], 0, s[40:41]
	global_load_dword v114, v[112:113], off
	v_lshl_add_u64 v[112:113], v[2:3], 0, s[40:41]
	global_load_dword v114, v[112:113], off
	v_lshl_add_u64 v[112:113], v[0:1], 0, s[40:41]
	global_load_dword v114, v[112:113], off
	s_mov_b64 s[40:41], 0x60000
	v_lshl_add_u64 v[112:113], v[6:7], 0, s[40:41]
	global_load_dword v114, v[112:113], off
	v_lshl_add_u64 v[112:113], v[4:5], 0, s[40:41]
	global_load_dword v114, v[112:113], off
	v_lshl_add_u64 v[112:113], v[2:3], 0, s[40:41]
	global_load_dword v114, v[112:113], off
	v_lshl_add_u64 v[112:113], v[0:1], 0, s[40:41]
	global_load_dword v114, v[112:113], off
	s_mov_b64 s[40:41], 0

; #define LAS __attribute__((address_space(3)))
; template <int MAP> __device__ __forceinline__ void transpose_item(const float* W, int K, int N, bf16_t* WT, const float* gain, LAS float* scr, int item, int lane) {
;     ...
; #pragma unroll 4
;     for (int i = 0; i < 16; ++i) { const int kk = 4 * i + lr; f32x4 v = *(const f32x4*)(W + (size_t)(k0 + kk) * N + n0 + lc); if (gain) v = v * gain[k0 + kk];
;         LAS float* d = scr + kk * 65 + lc; d[0] = v[0]; d[1] = v[1]; d[2] = v[2]; d[3] = v[3]; }
; __device__ __forceinline__ void phase_prologue(const Params& P, LAS unsigned char* lds) {
;     ...
;         const int per = 2 * I_G + I_DN + I_PG + I_PP; const int li = r / per; r -= li * per;
;         bf16_t* wgu = WB + (li ? W_GU1 : W_GU0); bf16_t* wdn = WB + (li ? W_DN1 : W_DN0); bf16_t* wpg = WB + (li ? W_PG1 : W_PG0); bf16_t* wpp = WB + (li ? W_PP1 : W_PP0);
;         if (r < I_G) { transpose_item<1>(P.in[18] + (size_t)li * 2048 * DFF, 2048, DFF, wgu, nffn + li * DM, scr, r, lane); continue; } r -= I_G;
;         if (r < I_G) { transpose_item<2>(P.in[19] + (size_t)li * 2048 * DFF, 2048, DFF, wgu, nffn + li * DM, scr, r, lane); continue; } r -= I_G;
;         if (r < I_DN) { transpose_item<0>(P.in[22] + (size_t)li * DFF * 2048, DFF, 2048, wdn, nullptr, scr, r, lane); continue; } r -= I_DN;
;         if (r < I_PG) { transpose_item<0>(P.in[24] + (size_t)li * 2048 * 2048, 2048, 2048, wpg, nple + li * DM, scr, r, lane); continue; } r -= I_PG;
;         transpose_item<0>(P.in[23] + (size_t)li * PLE_DIM * 2048, PLE_DIM, 2048, wpp, nullptr, scr, r, lane);
.LBB0_645:
	s_andn2_saveexec_b64 s[30:31], s[30:31]
	s_cbranch_execz .LBB0_657
	v_mov_b32_e32 v0, 0x800
	v_add_u16_e32 v5, 0xf500, v70
	v_cndmask_b32_e64 v4, 0, v0, s[38:39]
	v_mul_u32_u24_e32 v0, 0xba2f, v5
	v_lshrrev_b32_e32 v1, 22, v0
	s_movk_i32 s0, 0xffc0
	v_mul_lo_u16_e32 v1, 0x58, v1
	v_and_b32_sdwa v73, v0, s0 dst_sel:DWORD dst_unused:UNUSED_PAD src0_sel:WORD_1 src1_sel:DWORD
	s_mov_b32 s0, 0xffc0
	v_sub_u16_e32 v72, v5, v1
	v_and_b32_sdwa v6, v0, s0 dst_sel:DWORD dst_unused:UNUSED_PAD src0_sel:WORD_1 src1_sel:DWORD
	v_lshlrev_b32_e32 v180, 8, v72
	s_movk_i32 s2, 0x5800
	v_or_b32_e32 v2, v88, v6
	v_mad_u64_u32 v[0:1], s[0:1], v4, s2, v[180:181]
	v_mul_u32_u24_e32 v180, 0x5800, v2
	v_lshl_add_u64 v[2:3], v[0:1], 0, v[180:181]
	s_mov_b32 s0, 0x2e8ba2f
	v_lshl_add_u64 v[58:59], v[42:43], 0, v[2:3]
	v_mul_hi_u32 v2, v5, s0
	v_lshlrev_b32_e32 v2, 8, v2
	v_mov_b32_e32 v3, v181
	v_lshl_add_u64 v[60:61], v[44:45], 0, v[2:3]
	v_or_b32_e32 v2, v90, v6
	v_mul_u32_u24_e32 v2, 0x5800, v2
	v_lshl_add_u64 v[2:3], v[0:1], 0, v[2:3]
	v_lshl_add_u64 v[62:63], v[42:43], 0, v[2:3]
	v_or_b32_e32 v2, v91, v6
	v_mul_u32_u24_e32 v2, 0x5800, v2
	v_mov_b32_e32 v3, v181
	v_lshlrev_b32_e32 v180, 2, v4
	v_lshl_add_u64 v[2:3], v[0:1], 0, v[2:3]
	v_or_b32_e32 v4, v12, v6
	v_readlane_b32 s52, v253, 26
	v_lshl_add_u64 v[64:65], v[42:43], 0, v[2:3]
	v_lshlrev_b32_e32 v2, 2, v4
	v_mov_b32_e32 v3, v181
	v_readlane_b32 s60, v253, 34
	v_readlane_b32 s61, v253, 35
	v_mad_u64_u32 v[0:1], s[0:1], v4, s2, v[0:1]
	v_readlane_b32 s2, v250, 50
	v_lshlrev_b32_e32 v74, 6, v72
	v_lshl_add_u64 v[66:67], s[60:61], 0, v[2:3]
	v_lshl_add_u64 v[68:69], v[42:43], 0, v[0:1]
	s_mov_b64 s[34:35], 0
	v_mov_b32_e32 v75, v86
	v_readlane_b32 s3, v250, 51
	v_readlane_b32 s53, v253, 27
	v_readlane_b32 s54, v253, 28
	v_readlane_b32 s55, v253, 29
	v_readlane_b32 s56, v253, 30
	v_readlane_b32 s57, v253, 31
	v_readlane_b32 s58, v253, 32
	v_readlane_b32 s59, v253, 33
	v_readlane_b32 s62, v253, 36
	v_readlane_b32 s63, v253, 37
	v_readlane_b32 s64, v253, 38
	v_readlane_b32 s65, v253, 39
	v_readlane_b32 s66, v253, 40
	v_readlane_b32 s67, v253, 41
	s_mov_b64 s[34:35], 0x58000
	v_lshl_add_u64 v[112:113], v[68:69], 0, s[34:35]
	global_load_dword v114, v[112:113], off
	v_lshl_add_u64 v[112:113], v[64:65], 0, s[34:35]
	global_load_dword v114, v[112:113], off
	v_lshl_add_u64 v[112:113], v[62:63], 0, s[34:35]
	global_load_dword v114, v[112:113], off
	v_lshl_add_u64 v[112:113], v[58:59], 0, s[34:35]
	global_load_dword v114, v[112:113], off
	s_mov_b64 s[34:35], 0xb0000
	v_lshl_add_u64 v[112:113], v[68:69], 0, s[34:35]
	global_load_dword v114, v[112:113], off
	v_lshl_add_u64 v[112:113], v[64:65], 0, s[34:35]
	global_load_dword v114, v[112:113], off
	v_lshl_add_u64 v[112:113], v[62:63], 0, s[34:35]
	global_load_dword v114, v[112:113], off
	v_lshl_add_u64 v[112:113], v[58:59], 0, s[34:35]
	global_load_dword v114, v[112:113], off
	s_mov_b64 s[34:35], 0x108000
	v_lshl_add_u64 v[112:113], v[68:69], 0, s[34:35]
	global_load_dword v114, v[112:113], off
	v_lshl_add_u64 v[112:113], v[64:65], 0, s[34:35]
	global_load_dword v114, v[112:113], off
	v_lshl_add_u64 v[112:113], v[62:63], 0, s[34:35]
	global_load_dword v114, v[112:113], off
	v_lshl_add_u64 v[112:113], v[58:59], 0, s[34:35]
	global_load_dword v114, v[112:113], off
	s_mov_b64 s[34:35], 0
	s_branch .LBB0_648

; #define LAS __attribute__((address_space(3)))
; template <int MAP> __device__ __forceinline__ void transpose_item(const float* W, int K, int N, bf16_t* WT, const float* gain, LAS float* scr, int item, int lane) {
;     ...
; #pragma unroll 4
;     for (int i = 0; i < 16; ++i) { const int kk = 4 * i + lr; f32x4 v = *(const f32x4*)(W + (size_t)(k0 + kk) * N + n0 + lc); if (gain) v = v * gain[k0 + kk];
;         LAS float* d = scr + kk * 65 + lc; d[0] = v[0]; d[1] = v[1]; d[2] = v[2]; d[3] = v[3]; }
; __device__ __forceinline__ void phase_prologue(const Params& P, LAS unsigned char* lds) {
;     ...
;         const int per = 2 * I_G + I_DN + I_PG + I_PP; const int li = r / per; r -= li * per;
;         bf16_t* wgu = WB + (li ? W_GU1 : W_GU0); bf16_t* wdn = WB + (li ? W_DN1 : W_DN0); bf16_t* wpg = WB + (li ? W_PG1 : W_PG0); bf16_t* wpp = WB + (li ? W_PP1 : W_PP0);
;         if (r < I_G) { transpose_item<1>(P.in[18] + (size_t)li * 2048 * DFF, 2048, DFF, wgu, nffn + li * DM, scr, r, lane); continue; } r -= I_G;
;         if (r < I_G) { transpose_item<2>(P.in[19] + (size_t)li * 2048 * DFF, 2048, DFF, wgu, nffn + li * DM, scr, r, lane); continue; } r -= I_G;
;         if (r < I_DN) { transpose_item<0>(P.in[22] + (size_t)li * DFF * 2048, DFF, 2048, wdn, nullptr, scr, r, lane); continue; } r -= I_DN;
;         if (r < I_PG) { transpose_item<0>(P.in[24] + (size_t)li * 2048 * 2048, 2048, 2048, wpg, nple + li * DM, scr, r, lane); continue; } r -= I_PG;
;         transpose_item<0>(P.in[23] + (size_t)li * PLE_DIM * 2048, PLE_DIM, 2048, wpp, nullptr, scr, r, lane);
.LBB0_658:
	s_andn2_saveexec_b64 s[28:29], s[28:29]
	s_cbranch_execz .LBB0_670
	v_mov_b32_e32 v0, 0x800
	v_cndmask_b32_e64 v2, 0, v0, s[38:39]
	s_movk_i32 s0, 0xba3
	v_mul_hi_u32_u24_e32 v1, 0x5800, v2
	v_mul_u32_u24_e32 v0, 0x5800, v2
	v_lshlrev_b32_e32 v180, 2, v2
	v_mul_i32_i24_sdwa v2, sext(v70), s0 dst_sel:DWORD dst_unused:UNUSED_PAD src0_sel:WORD_0 src1_sel:DWORD
	v_lshrrev_b32_e32 v3, 31, v2
	v_ashrrev_i32_e32 v2, 18, v2
	v_add_u16_e32 v2, v2, v3
	v_mul_lo_u16_e32 v3, 0x58, v2
	v_sub_u16_e32 v95, v70, v3
	v_lshlrev_b32_sdwa v60, v210, sext(v2) dst_sel:DWORD dst_unused:UNUSED_PAD src0_sel:DWORD src1_sel:WORD_0
	v_lshlrev_b32_sdwa v62, v210, sext(v95) dst_sel:DWORD dst_unused:UNUSED_PAD src0_sel:DWORD src1_sel:WORD_0
	v_ashrrev_i32_e32 v63, 31, v62
	v_ashrrev_i32_e32 v61, 31, v60
	v_or_b32_e32 v4, v88, v60
	s_movk_i32 s2, 0x5800
	v_or_b32_e32 v2, v12, v60
	v_mov_b32_e32 v3, v61
	v_mad_i64_i32 v[4:5], s[0:1], v4, s2, v[0:1]
	v_lshlrev_b64 v[6:7], 2, v[62:63]
	v_lshl_add_u64 v[4:5], v[4:5], 0, v[6:7]
	v_lshlrev_b64 v[66:67], 2, v[2:3]
	v_or_b32_e32 v3, v90, v60
	v_lshl_add_u64 v[64:65], v[46:47], 0, v[4:5]
	v_mad_i64_i32 v[4:5], s[0:1], v3, s2, v[0:1]
	v_lshl_add_u64 v[4:5], v[4:5], 0, v[6:7]
	v_or_b32_e32 v3, v91, v60
	v_readlane_b32 s52, v253, 26
	v_lshl_add_u64 v[68:69], v[46:47], 0, v[4:5]
	v_mad_i64_i32 v[4:5], s[0:1], v3, s2, v[0:1]
	v_mad_i64_i32 v[0:1], s[0:1], v2, s2, v[0:1]
	v_readlane_b32 s60, v253, 34
	v_readlane_b32 s61, v253, 35
	v_lshl_add_u64 v[4:5], v[4:5], 0, v[6:7]
	v_ashrrev_i32_e32 v3, 31, v2
	v_lshl_add_u64 v[0:1], v[0:1], 0, v[6:7]
	v_readlane_b32 s2, v250, 50
	v_lshl_add_u64 v[58:59], s[60:61], 0, v[180:181]
	v_lshl_add_u64 v[70:71], v[46:47], 0, v[4:5]
	v_lshlrev_b64 v[72:73], 2, v[2:3]
	v_lshl_add_u64 v[74:75], v[46:47], 0, v[0:1]
	s_mov_b64 s[30:31], 0
	v_mov_b32_e32 v63, v86
	v_readlane_b32 s3, v250, 51
	v_readlane_b32 s53, v253, 27
	v_readlane_b32 s54, v253, 28
	v_readlane_b32 s55, v253, 29
	v_readlane_b32 s56, v253, 30
	v_readlane_b32 s57, v253, 31
	v_readlane_b32 s58, v253, 32
	v_readlane_b32 s59, v253, 33
	v_readlane_b32 s62, v253, 36
	v_readlane_b32 s63, v253, 37
	v_readlane_b32 s64, v253, 38
	v_readlane_b32 s65, v253, 39
	v_readlane_b32 s66, v253, 40
	v_readlane_b32 s67, v253, 41
	s_mov_b64 s[30:31], 0x58000
	v_lshl_add_u64 v[112:113], v[74:75], 0, s[30:31]
	global_load_dword v114, v[112:113], off
	v_lshl_add_u64 v[112:113], v[70:71], 0, s[30:31]
	global_load_dword v114, v[112:113], off
	v_lshl_add_u64 v[112:113], v[68:69], 0, s[30:31]
	global_load_dword v114, v[112:113], off
	v_lshl_add_u64 v[112:113], v[64:65], 0, s[30:31]
	global_load_dword v114, v[112:113], off
	s_mov_b64 s[30:31], 0xb0000
	v_lshl_add_u64 v[112:113], v[74:75], 0, s[30:31]
	global_load_dword v114, v[112:113], off
	v_lshl_add_u64 v[112:113], v[70:71], 0, s[30:31]
	global_load_dword v114, v[112:113], off
	v_lshl_add_u64 v[112:113], v[68:69], 0, s[30:31]
	global_load_dword v114, v[112:113], off
	v_lshl_add_u64 v[112:113], v[64:65], 0, s[30:31]
	global_load_dword v114, v[112:113], off
	s_mov_b64 s[30:31], 0x108000
	v_lshl_add_u64 v[112:113], v[74:75], 0, s[30:31]
	global_load_dword v114, v[112:113], off
	v_lshl_add_u64 v[112:113], v[70:71], 0, s[30:31]
	global_load_dword v114, v[112:113], off
	v_lshl_add_u64 v[112:113], v[68:69], 0, s[30:31]
	global_load_dword v114, v[112:113], off
	v_lshl_add_u64 v[112:113], v[64:65], 0, s[30:31]
	global_load_dword v114, v[112:113], off
	s_mov_b64 s[30:31], 0
	s_branch .LBB0_661

; #define LAS __attribute__((address_space(3)))
; template <int MAP> __device__ __forceinline__ void transpose_item(const float* W, int K, int N, bf16_t* WT, const float* gain, LAS float* scr, int item, int lane) {
;     ...
; #pragma unroll 4
;     for (int i = 0; i < 16; ++i) { const int kk = 4 * i + lr; f32x4 v = *(const f32x4*)(W + (size_t)(k0 + kk) * N + n0 + lc); if (gain) v = v * gain[k0 + kk];
;         LAS float* d = scr + kk * 65 + lc; d[0] = v[0]; d[1] = v[1]; d[2] = v[2]; d[3] = v[3]; }
; __device__ __forceinline__ void phase_prologue(const Params& P, LAS unsigned char* lds) {
;     ...
;         if (r < I_EOUT) { transpose_item<0>(P.in[15], 2048, 2048, WB + W_EOUT, nullptr, scr, r, lane); continue; } r -= I_EOUT;
;         if (r < I_OIN) { transpose_item<0>(P.in[16], 2048, ODD_IN, WB + W_OIN, nmix + DM, scr, r, lane); continue; } r -= I_OIN;
;         if (r < I_OOUT) { transpose_item<0>(P.in[17], 4096, 2048, WB + W_OOUT, nullptr, scr, r, lane); continue; } r -= I_OOUT;
.LBB0_671:
	s_andn2_saveexec_b64 s[0:1], s[26:27]
	s_cbranch_execz .LBB0_675
	v_and_b32_e32 v7, 0x1ffc0, v92
	v_or_b32_e32 v0, v88, v7
	v_lshl_or_b32 v180, v0, 13, v6
	v_or_b32_e32 v2, v90, v7
	v_lshl_add_u64 v[0:1], v[48:49], 0, v[180:181]
	v_lshl_or_b32 v180, v2, 13, v6
	v_or_b32_e32 v4, v91, v7
	v_lshl_add_u64 v[2:3], v[48:49], 0, v[180:181]
	v_lshl_or_b32 v180, v4, 13, v6
	v_or_b32_e32 v7, v12, v7
	v_lshl_add_u64 v[4:5], v[48:49], 0, v[180:181]
	v_lshl_or_b32 v180, v7, 13, v6
	v_lshl_add_u64 v[6:7], v[48:49], 0, v[180:181]
	s_mov_b64 s[26:27], 0
	v_mov_b32_e32 v56, v86
	s_mov_b64 s[26:27], 0x20000
	v_lshl_add_u64 v[112:113], v[6:7], 0, s[26:27]
	global_load_dword v114, v[112:113], off
	v_lshl_add_u64 v[112:113], v[4:5], 0, s[26:27]
	global_load_dword v114, v[112:113], off
	v_lshl_add_u64 v[112:113], v[2:3], 0, s[26:27]
	global_load_dword v114, v[112:113], off
	v_lshl_add_u64 v[112:113], v[0:1], 0, s[26:27]
	global_load_dword v114, v[112:113], off
	s_mov_b64 s[26:27], 0x40000
	v_lshl_add_u64 v[112:113], v[6:7], 0, s[26:27]
	global_load_dword v114, v[112:113], off
	v_lshl_add_u64 v[112:113], v[4:5], 0, s[26:27]
	global_load_dword v114, v[112:113], off
	v_lshl_add_u64 v[112:113], v[2:3], 0, s[26:27]
	global_load_dword v114, v[112:113], off
	v_lshl_add_u64 v[112:113], v[0:1], 0, s[26:27]
	global_load_dword v114, v[112:113], off
	s_mov_b64 s[26:27], 0x60000
	v_lshl_add_u64 v[112:113], v[6:7], 0, s[26:27]
	global_load_dword v114, v[112:113], off
	v_lshl_add_u64 v[112:113], v[4:5], 0, s[26:27]
	global_load_dword v114, v[112:113], off
	v_lshl_add_u64 v[112:113], v[2:3], 0, s[26:27]
	global_load_dword v114, v[112:113], off
	v_lshl_add_u64 v[112:113], v[0:1], 0, s[26:27]
	global_load_dword v114, v[112:113], off
	s_mov_b64 s[26:27], 0

; #define LAS __attribute__((address_space(3)))
; template <int MAP> __device__ __forceinline__ void transpose_item(const float* W, int K, int N, bf16_t* WT, const float* gain, LAS float* scr, int item, int lane) {
;     const int nblk = N / 64, kb = item / nblk, nb = item % nblk, k0 = 64 * kb, n0 = 64 * nb;
;     const int lr = lane >> 4, lc = (lane & 15) * 4;
; #pragma unroll 4
;     for (int i = 0; i < 16; ++i) { const int kk = 4 * i + lr; f32x4 v = *(const f32x4*)(W + (size_t)(k0 + kk) * N + n0 + lc); if (gain) v = v * gain[k0 + kk];
;         LAS float* d = scr + kk * 65 + lc; d[0] = v[0]; d[1] = v[1]; d[2] = v[2]; d[3] = v[3]; }
.LBB0_681:
	s_andn2_saveexec_b64 s[0:1], s[20:21]
	s_cbranch_execz .LBB0_685
	v_and_b32_e32 v7, 0x1ffc0, v93
	v_or_b32_e32 v0, v88, v7
	v_lshl_or_b32 v180, v0, 13, v6
	v_or_b32_e32 v2, v90, v7
	v_lshl_add_u64 v[0:1], v[50:51], 0, v[180:181]
	v_lshl_or_b32 v180, v2, 13, v6
	v_or_b32_e32 v4, v91, v7
	v_lshl_add_u64 v[2:3], v[50:51], 0, v[180:181]
	v_lshl_or_b32 v180, v4, 13, v6
	v_or_b32_e32 v7, v12, v7
	v_lshl_add_u64 v[4:5], v[50:51], 0, v[180:181]
	v_lshl_or_b32 v180, v7, 13, v6
	v_lshl_add_u64 v[6:7], v[50:51], 0, v[180:181]
	s_mov_b64 s[20:21], 0
	v_mov_b32_e32 v56, v86
	s_mov_b64 s[20:21], 0x20000
	v_lshl_add_u64 v[112:113], v[6:7], 0, s[20:21]
	global_load_dword v114, v[112:113], off
	v_lshl_add_u64 v[112:113], v[4:5], 0, s[20:21]
	global_load_dword v114, v[112:113], off
	v_lshl_add_u64 v[112:113], v[2:3], 0, s[20:21]
	global_load_dword v114, v[112:113], off
	v_lshl_add_u64 v[112:113], v[0:1], 0, s[20:21]
	global_load_dword v114, v[112:113], off
	s_mov_b64 s[20:21], 0x40000
	v_lshl_add_u64 v[112:113], v[6:7], 0, s[20:21]
	global_load_dword v114, v[112:113], off
	v_lshl_add_u64 v[112:113], v[4:5], 0, s[20:21]
	global_load_dword v114, v[112:113], off
	v_lshl_add_u64 v[112:113], v[2:3], 0, s[20:21]
	global_load_dword v114, v[112:113], off
	v_lshl_add_u64 v[112:113], v[0:1], 0, s[20:21]
	global_load_dword v114, v[112:113], off
	s_mov_b64 s[20:21], 0x60000
	v_lshl_add_u64 v[112:113], v[6:7], 0, s[20:21]
	global_load_dword v114, v[112:113], off
	v_lshl_add_u64 v[112:113], v[4:5], 0, s[20:21]
	global_load_dword v114, v[112:113], off
	v_lshl_add_u64 v[112:113], v[2:3], 0, s[20:21]
	global_load_dword v114, v[112:113], off
	v_lshl_add_u64 v[112:113], v[0:1], 0, s[20:21]
	global_load_dword v114, v[112:113], off
	s_mov_b64 s[20:21], 0

; #define LAS __attribute__((address_space(3)))
; template <int MAP> __device__ __forceinline__ void transpose_item(const float* W, int K, int N, bf16_t* WT, const float* gain, LAS float* scr, int item, int lane) {
;     const int nblk = N / 64, kb = item / nblk, nb = item % nblk, k0 = 64 * kb, n0 = 64 * nb;
;     const int lr = lane >> 4, lc = (lane & 15) * 4;
; #pragma unroll 4
;     for (int i = 0; i < 16; ++i) { const int kk = 4 * i + lr; f32x4 v = *(const f32x4*)(W + (size_t)(k0 + kk) * N + n0 + lc); if (gain) v = v * gain[k0 + kk];
;         LAS float* d = scr + kk * 65 + lc; d[0] = v[0]; d[1] = v[1]; d[2] = v[2]; d[3] = v[3]; }
; __device__ __forceinline__ void phase_prologue(const Params& P, LAS unsigned char* lds) {
;     ...
;         if (r < I_UKV) { transpose_item<0>(P.in[11], 512, 2048, WB + W_UKV, P.in[9], scr, r, lane); continue; } r -= I_UKV;
.LBB0_686:
	s_andn2_saveexec_b64 s[14:15], s[14:15]
	s_cbranch_execz .LBB0_698
	v_bfe_u32 v0, v94, 6, 3
	v_lshlrev_b32_e32 v1, 6, v0
	v_or_b32_e32 v2, v88, v1
	v_lshl_or_b32 v180, v2, 13, v6
	v_lshl_or_b32 v58, v0, 8, v36
	v_or_b32_e32 v0, v90, v1
	v_lshl_add_u64 v[56:57], v[52:53], 0, v[180:181]
	v_lshl_or_b32 v180, v0, 13, v6
	v_or_b32_e32 v0, v91, v1
	v_lshl_add_u64 v[60:61], v[52:53], 0, v[180:181]
	v_lshl_or_b32 v180, v0, 13, v6
	v_or_b32_e32 v0, v12, v1
	v_readlane_b32 s52, v250, 62
	v_lshl_add_u64 v[62:63], v[52:53], 0, v[180:181]
	v_lshlrev_b32_e32 v180, 2, v0
	v_lshl_or_b32 v0, v0, 13, v6
	v_mov_b32_e32 v1, v181
	v_readlane_b32 s54, v251, 0
	v_readlane_b32 s55, v251, 1
	v_mov_b32_e32 v59, v37
	v_lshl_add_u64 v[64:65], v[52:53], 0, v[0:1]
	s_mov_b64 s[20:21], 0
	s_mov_b64 s[24:25], s[54:55]
	v_mov_b32_e32 v68, v86
	v_readlane_b32 s53, v250, 63
	v_readlane_b32 s56, v251, 2
	v_readlane_b32 s57, v251, 3
	v_readlane_b32 s58, v251, 4
	v_readlane_b32 s59, v251, 5
	v_readlane_b32 s60, v251, 6
	v_readlane_b32 s61, v251, 7
	v_readlane_b32 s62, v251, 8
	v_readlane_b32 s63, v251, 9
	v_readlane_b32 s64, v251, 10
	v_readlane_b32 s65, v251, 11
	v_readlane_b32 s66, v251, 12
	v_readlane_b32 s67, v251, 13
	s_mov_b64 s[20:21], 0x20000
	v_lshl_add_u64 v[112:113], v[64:65], 0, s[20:21]
	global_load_dword v114, v[112:113], off
	v_lshl_add_u64 v[112:113], v[62:63], 0, s[20:21]
	global_load_dword v114, v[112:113], off
	v_lshl_add_u64 v[112:113], v[60:61], 0, s[20:21]
	global_load_dword v114, v[112:113], off
	v_lshl_add_u64 v[112:113], v[56:57], 0, s[20:21]
	global_load_dword v114, v[112:113], off
	s_mov_b64 s[20:21], 0x40000
	v_lshl_add_u64 v[112:113], v[64:65], 0, s[20:21]
	global_load_dword v114, v[112:113], off
	v_lshl_add_u64 v[112:113], v[62:63], 0, s[20:21]
	global_load_dword v114, v[112:113], off
	v_lshl_add_u64 v[112:113], v[60:61], 0, s[20:21]
	global_load_dword v114, v[112:113], off
	v_lshl_add_u64 v[112:113], v[56:57], 0, s[20:21]
	global_load_dword v114, v[112:113], off
	s_mov_b64 s[20:21], 0x60000
	v_lshl_add_u64 v[112:113], v[64:65], 0, s[20:21]
	global_load_dword v114, v[112:113], off
	v_lshl_add_u64 v[112:113], v[62:63], 0, s[20:21]
	global_load_dword v114, v[112:113], off
	v_lshl_add_u64 v[112:113], v[60:61], 0, s[20:21]
	global_load_dword v114, v[112:113], off
	v_lshl_add_u64 v[112:113], v[56:57], 0, s[20:21]
	global_load_dword v114, v[112:113], off
	s_mov_b64 s[20:21], 0
	s_branch .LBB0_689

; #define LAS __attribute__((address_space(3)))
; template <int MAP> __device__ __forceinline__ void transpose_item(const float* W, int K, int N, bf16_t* WT, const float* gain, LAS float* scr, int item, int lane) {
;     const int nblk = N / 64, kb = item / nblk, nb = item % nblk, k0 = 64 * kb, n0 = 64 * nb;
;     const int lr = lane >> 4, lc = (lane & 15) * 4;
; #pragma unroll 4
;     for (int i = 0; i < 16; ++i) { const int kk = 4 * i + lr; f32x4 v = *(const f32x4*)(W + (size_t)(k0 + kk) * N + n0 + lc); if (gain) v = v * gain[k0 + kk];
;         LAS float* d = scr + kk * 65 + lc; d[0] = v[0]; d[1] = v[1]; d[2] = v[2]; d[3] = v[3]; }
; __device__ __forceinline__ void phase_prologue(const Params& P, LAS unsigned char* lds) {
;     ...
;         if (r < I_UQ) { transpose_item<0>(P.in[10], 512, 1536, WB + W_UQ, P.in[8], scr, r, lane); continue; } r -= I_UQ;
.LBB0_699:
	s_andn2_saveexec_b64 s[12:13], s[12:13]
	s_cbranch_execz .LBB0_711
	v_subrev_u16_e32 v0, 32, v13
	v_and_b32_e32 v4, 0xff, v0
	v_mul_lo_u16_e32 v1, 0xab, v4
	v_lshrrev_b16_e32 v1, 12, v1
	v_mul_lo_u16_e32 v2, 24, v1
	v_lshlrev_b32_e32 v69, 6, v1
	v_sub_u16_e32 v0, v0, v2
	v_or_b32_e32 v2, v88, v69
	v_lshlrev_b32_sdwa v68, v210, v0 dst_sel:DWORD dst_unused:UNUSED_PAD src0_sel:DWORD src1_sel:BYTE_0
	v_lshlrev_b32_sdwa v0, v248, v0 dst_sel:DWORD dst_unused:UNUSED_PAD src0_sel:DWORD src1_sel:BYTE_0
	v_mov_b32_e32 v1, v181
	v_mul_u32_u24_e32 v180, 0x1800, v2
	v_lshl_add_u64 v[2:3], v[0:1], 0, v[180:181]
	s_mov_b32 s0, 0xaaaaaab
	v_lshl_add_u64 v[56:57], v[54:55], 0, v[2:3]
	v_mul_hi_u32 v2, v4, s0
	v_lshl_or_b32 v58, v2, 8, v36
	v_or_b32_e32 v2, v90, v69
	v_mul_u32_u24_e32 v180, 0x1800, v2
	v_lshl_add_u64 v[2:3], v[0:1], 0, v[180:181]
	v_lshl_add_u64 v[60:61], v[54:55], 0, v[2:3]
	v_or_b32_e32 v2, v91, v69
	v_mul_u32_u24_e32 v180, 0x1800, v2
	v_lshl_add_u64 v[2:3], v[0:1], 0, v[180:181]
	v_lshl_add_u64 v[62:63], v[54:55], 0, v[2:3]
	v_or_b32_e32 v2, v12, v69
	s_movk_i32 s0, 0x1800
	v_readlane_b32 s52, v250, 62
	v_mad_u64_u32 v[0:1], s[0:1], v2, s0, v[0:1]
	v_readlane_b32 s53, v250, 63
	v_mov_b32_e32 v59, v37
	v_lshlrev_b32_e32 v180, 2, v2
	v_lshl_add_u64 v[64:65], v[54:55], 0, v[0:1]
	s_mov_b64 s[14:15], 0
	s_mov_b64 s[20:21], s[52:53]
	v_mov_b32_e32 v70, v86
	v_readlane_b32 s54, v251, 0
	v_readlane_b32 s55, v251, 1
	v_readlane_b32 s56, v251, 2
	v_readlane_b32 s57, v251, 3
	v_readlane_b32 s58, v251, 4
	v_readlane_b32 s59, v251, 5
	v_readlane_b32 s60, v251, 6
	v_readlane_b32 s61, v251, 7
	v_readlane_b32 s62, v251, 8
	v_readlane_b32 s63, v251, 9
	v_readlane_b32 s64, v251, 10
	v_readlane_b32 s65, v251, 11
	v_readlane_b32 s66, v251, 12
	v_readlane_b32 s67, v251, 13
	s_mov_b64 s[14:15], 0x18000
	v_lshl_add_u64 v[112:113], v[64:65], 0, s[14:15]
	global_load_dword v114, v[112:113], off
	v_lshl_add_u64 v[112:113], v[62:63], 0, s[14:15]
	global_load_dword v114, v[112:113], off
	v_lshl_add_u64 v[112:113], v[60:61], 0, s[14:15]
	global_load_dword v114, v[112:113], off
	v_lshl_add_u64 v[112:113], v[56:57], 0, s[14:15]
	global_load_dword v114, v[112:113], off
	s_mov_b64 s[14:15], 0x30000
	v_lshl_add_u64 v[112:113], v[64:65], 0, s[14:15]
	global_load_dword v114, v[112:113], off
	v_lshl_add_u64 v[112:113], v[62:63], 0, s[14:15]
	global_load_dword v114, v[112:113], off
	v_lshl_add_u64 v[112:113], v[60:61], 0, s[14:15]
	global_load_dword v114, v[112:113], off
	v_lshl_add_u64 v[112:113], v[56:57], 0, s[14:15]
	global_load_dword v114, v[112:113], off
	s_mov_b64 s[14:15], 0x48000
	v_lshl_add_u64 v[112:113], v[64:65], 0, s[14:15]
	global_load_dword v114, v[112:113], off
	v_lshl_add_u64 v[112:113], v[62:63], 0, s[14:15]
	global_load_dword v114, v[112:113], off
	v_lshl_add_u64 v[112:113], v[60:61], 0, s[14:15]
	global_load_dword v114, v[112:113], off
	v_lshl_add_u64 v[112:113], v[56:57], 0, s[14:15]
	global_load_dword v114, v[112:113], off
	s_mov_b64 s[14:15], 0
	s_branch .LBB0_702
